# v61 plus unrolled score loop, shared queue counter and the select fast path (rank counter moved off v249, which the queue carry uses)
# speedup vs baseline: 1.0133x; 1.0046x over previous
.Lsel_D2_done:
	s_waitcnt lgkmcnt(0)
	v_lshl_add_u32 v241, v198, 3, s4
	ds_read_b64 v[242:243], v241
	s_waitcnt lgkmcnt(0)
	v_mov_b32_e32 v248, v242
	v_add_f32_e32 v243, 0, v243
	v_ashrrev_i32_e32 v186, 31, v243
	v_or_b32_e32 v186, 0x80000000, v186
	v_xor_b32_e32 v243, v243, v186
	v_not_b32_e32 v242, v242
	v_cmp_gt_u32_e32 vcc, s82, v198
	v_mov_b32_e32 v36, 0
	v_mov_b32_e32 v187, 0
	v_cndmask_b32_e32 v243, 0, v243, vcc
	v_cndmask_b32_e32 v242, 0, v242, vcc
	s_nop 0
	v_readlane_b32 s72, v242, 0
	v_readlane_b32 s73, v243, 0
	v_readlane_b32 s74, v242, 1
	v_readlane_b32 s75, v243, 1
	v_readlane_b32 s76, v242, 2
	v_readlane_b32 s77, v243, 2
	v_readlane_b32 s78, v242, 3
	v_readlane_b32 s79, v243, 3
	v_cmp_gt_u64_e64 vcc, s[72:73], v[242:243]
	v_cmp_gt_u64_e64 s[0:1], s[74:75], v[242:243]
	v_cmp_gt_u64_e64 s[2:3], s[76:77], v[242:243]
	v_cmp_gt_u64_e64 s[4:5], s[78:79], v[242:243]
	v_addc_co_u32_e64 v36, vcc, 0, v36, vcc
	v_addc_co_u32_e64 v187, s[0:1], 0, v187, s[0:1]
	v_addc_co_u32_e64 v36, s[2:3], 0, v36, s[2:3]
	v_addc_co_u32_e64 v187, s[4:5], 0, v187, s[4:5]
	s_cmpk_le_u32 s82, 4
	s_cbranch_scc1 .Lsel_rank_done
	v_readlane_b32 s72, v242, 4
	v_readlane_b32 s73, v243, 4
	v_readlane_b32 s74, v242, 5
	v_readlane_b32 s75, v243, 5
	v_readlane_b32 s76, v242, 6
	v_readlane_b32 s77, v243, 6
	v_readlane_b32 s78, v242, 7
	v_readlane_b32 s79, v243, 7
	v_cmp_gt_u64_e64 vcc, s[72:73], v[242:243]
	v_cmp_gt_u64_e64 s[0:1], s[74:75], v[242:243]
	v_cmp_gt_u64_e64 s[2:3], s[76:77], v[242:243]
	v_cmp_gt_u64_e64 s[4:5], s[78:79], v[242:243]
	v_addc_co_u32_e64 v36, vcc, 0, v36, vcc
	v_addc_co_u32_e64 v187, s[0:1], 0, v187, s[0:1]
	v_addc_co_u32_e64 v36, s[2:3], 0, v36, s[2:3]
	v_addc_co_u32_e64 v187, s[4:5], 0, v187, s[4:5]
	s_cmpk_le_u32 s82, 8
	s_cbranch_scc1 .Lsel_rank_done
	v_readlane_b32 s72, v242, 8
	v_readlane_b32 s73, v243, 8
	v_readlane_b32 s74, v242, 9
	v_readlane_b32 s75, v243, 9
	v_readlane_b32 s76, v242, 10
	v_readlane_b32 s77, v243, 10
	v_readlane_b32 s78, v242, 11
	v_readlane_b32 s79, v243, 11
	v_cmp_gt_u64_e64 vcc, s[72:73], v[242:243]
	v_cmp_gt_u64_e64 s[0:1], s[74:75], v[242:243]
	v_cmp_gt_u64_e64 s[2:3], s[76:77], v[242:243]
	v_cmp_gt_u64_e64 s[4:5], s[78:79], v[242:243]
	v_addc_co_u32_e64 v36, vcc, 0, v36, vcc
	v_addc_co_u32_e64 v187, s[0:1], 0, v187, s[0:1]
	v_addc_co_u32_e64 v36, s[2:3], 0, v36, s[2:3]
	v_addc_co_u32_e64 v187, s[4:5], 0, v187, s[4:5]
	s_cmpk_le_u32 s82, 12
	s_cbranch_scc1 .Lsel_rank_done
	v_readlane_b32 s72, v242, 12
	v_readlane_b32 s73, v243, 12
	v_readlane_b32 s74, v242, 13
	v_readlane_b32 s75, v243, 13
	v_readlane_b32 s76, v242, 14
	v_readlane_b32 s77, v243, 14
	v_readlane_b32 s78, v242, 15
	v_readlane_b32 s79, v243, 15
	v_cmp_gt_u64_e64 vcc, s[72:73], v[242:243]
	v_cmp_gt_u64_e64 s[0:1], s[74:75], v[242:243]
	v_cmp_gt_u64_e64 s[2:3], s[76:77], v[242:243]
	v_cmp_gt_u64_e64 s[4:5], s[78:79], v[242:243]
	v_addc_co_u32_e64 v36, vcc, 0, v36, vcc
	v_addc_co_u32_e64 v187, s[0:1], 0, v187, s[0:1]
	v_addc_co_u32_e64 v36, s[2:3], 0, v36, s[2:3]
	v_addc_co_u32_e64 v187, s[4:5], 0, v187, s[4:5]
	s_cmpk_le_u32 s82, 16
	s_cbranch_scc1 .Lsel_rank_done
	v_readlane_b32 s72, v242, 16
	v_readlane_b32 s73, v243, 16
	v_readlane_b32 s74, v242, 17
	v_readlane_b32 s75, v243, 17
	v_readlane_b32 s76, v242, 18
	v_readlane_b32 s77, v243, 18
	v_readlane_b32 s78, v242, 19
	v_readlane_b32 s79, v243, 19
	v_cmp_gt_u64_e64 vcc, s[72:73], v[242:243]
	v_cmp_gt_u64_e64 s[0:1], s[74:75], v[242:243]
	v_cmp_gt_u64_e64 s[2:3], s[76:77], v[242:243]
	v_cmp_gt_u64_e64 s[4:5], s[78:79], v[242:243]
	v_addc_co_u32_e64 v36, vcc, 0, v36, vcc
	v_addc_co_u32_e64 v187, s[0:1], 0, v187, s[0:1]
	v_addc_co_u32_e64 v36, s[2:3], 0, v36, s[2:3]
	v_addc_co_u32_e64 v187, s[4:5], 0, v187, s[4:5]
	s_cmpk_le_u32 s82, 20
	s_cbranch_scc1 .Lsel_rank_done
	v_readlane_b32 s72, v242, 20
	v_readlane_b32 s73, v243, 20
	v_readlane_b32 s74, v242, 21
	v_readlane_b32 s75, v243, 21
	v_readlane_b32 s76, v242, 22
	v_readlane_b32 s77, v243, 22
	v_readlane_b32 s78, v242, 23
	v_readlane_b32 s79, v243, 23
	v_cmp_gt_u64_e64 vcc, s[72:73], v[242:243]
	v_cmp_gt_u64_e64 s[0:1], s[74:75], v[242:243]
	v_cmp_gt_u64_e64 s[2:3], s[76:77], v[242:243]
	v_cmp_gt_u64_e64 s[4:5], s[78:79], v[242:243]
	v_addc_co_u32_e64 v36, vcc, 0, v36, vcc
	v_addc_co_u32_e64 v187, s[0:1], 0, v187, s[0:1]
	v_addc_co_u32_e64 v36, s[2:3], 0, v36, s[2:3]
	v_addc_co_u32_e64 v187, s[4:5], 0, v187, s[4:5]
	s_cmpk_le_u32 s82, 24
	s_cbranch_scc1 .Lsel_rank_done
	v_readlane_b32 s72, v242, 24
	v_readlane_b32 s73, v243, 24
	v_readlane_b32 s74, v242, 25
	v_readlane_b32 s75, v243, 25
	v_readlane_b32 s76, v242, 26
	v_readlane_b32 s77, v243, 26
	v_readlane_b32 s78, v242, 27
	v_readlane_b32 s79, v243, 27
	v_cmp_gt_u64_e64 vcc, s[72:73], v[242:243]
	v_cmp_gt_u64_e64 s[0:1], s[74:75], v[242:243]
	v_cmp_gt_u64_e64 s[2:3], s[76:77], v[242:243]
	v_cmp_gt_u64_e64 s[4:5], s[78:79], v[242:243]
	v_addc_co_u32_e64 v36, vcc, 0, v36, vcc
	v_addc_co_u32_e64 v187, s[0:1], 0, v187, s[0:1]
	v_addc_co_u32_e64 v36, s[2:3], 0, v36, s[2:3]
	v_addc_co_u32_e64 v187, s[4:5], 0, v187, s[4:5]
	s_cmpk_le_u32 s82, 28
	s_cbranch_scc1 .Lsel_rank_done
	v_readlane_b32 s72, v242, 28
	v_readlane_b32 s73, v243, 28
	v_readlane_b32 s74, v242, 29
	v_readlane_b32 s75, v243, 29
	v_readlane_b32 s76, v242, 30
	v_readlane_b32 s77, v243, 30
	v_readlane_b32 s78, v242, 31
	v_readlane_b32 s79, v243, 31
	v_cmp_gt_u64_e64 vcc, s[72:73], v[242:243]
	v_cmp_gt_u64_e64 s[0:1], s[74:75], v[242:243]
	v_cmp_gt_u64_e64 s[2:3], s[76:77], v[242:243]
	v_cmp_gt_u64_e64 s[4:5], s[78:79], v[242:243]
	v_addc_co_u32_e64 v36, vcc, 0, v36, vcc
	v_addc_co_u32_e64 v187, s[0:1], 0, v187, s[0:1]
	v_addc_co_u32_e64 v36, s[2:3], 0, v36, s[2:3]
	v_addc_co_u32_e64 v187, s[4:5], 0, v187, s[4:5]
	s_cmpk_le_u32 s82, 32
	s_cbranch_scc1 .Lsel_rank_done
	v_readlane_b32 s72, v242, 32
	v_readlane_b32 s73, v243, 32
	v_readlane_b32 s74, v242, 33
	v_readlane_b32 s75, v243, 33
	v_readlane_b32 s76, v242, 34
	v_readlane_b32 s77, v243, 34
	v_readlane_b32 s78, v242, 35
	v_readlane_b32 s79, v243, 35
	v_cmp_gt_u64_e64 vcc, s[72:73], v[242:243]
	v_cmp_gt_u64_e64 s[0:1], s[74:75], v[242:243]
	v_cmp_gt_u64_e64 s[2:3], s[76:77], v[242:243]
	v_cmp_gt_u64_e64 s[4:5], s[78:79], v[242:243]
	v_addc_co_u32_e64 v36, vcc, 0, v36, vcc
	v_addc_co_u32_e64 v187, s[0:1], 0, v187, s[0:1]
	v_addc_co_u32_e64 v36, s[2:3], 0, v36, s[2:3]
	v_addc_co_u32_e64 v187, s[4:5], 0, v187, s[4:5]
	s_cmpk_le_u32 s82, 36
	s_cbranch_scc1 .Lsel_rank_done
	v_readlane_b32 s72, v242, 36
	v_readlane_b32 s73, v243, 36
	v_readlane_b32 s74, v242, 37
	v_readlane_b32 s75, v243, 37
	v_readlane_b32 s76, v242, 38
	v_readlane_b32 s77, v243, 38
	v_readlane_b32 s78, v242, 39
	v_readlane_b32 s79, v243, 39
	v_cmp_gt_u64_e64 vcc, s[72:73], v[242:243]
	v_cmp_gt_u64_e64 s[0:1], s[74:75], v[242:243]
	v_cmp_gt_u64_e64 s[2:3], s[76:77], v[242:243]
	v_cmp_gt_u64_e64 s[4:5], s[78:79], v[242:243]
	v_addc_co_u32_e64 v36, vcc, 0, v36, vcc
	v_addc_co_u32_e64 v187, s[0:1], 0, v187, s[0:1]
	v_addc_co_u32_e64 v36, s[2:3], 0, v36, s[2:3]
	v_addc_co_u32_e64 v187, s[4:5], 0, v187, s[4:5]
	s_cmpk_le_u32 s82, 40
	s_cbranch_scc1 .Lsel_rank_done
	v_readlane_b32 s72, v242, 40
	v_readlane_b32 s73, v243, 40
	v_readlane_b32 s74, v242, 41
	v_readlane_b32 s75, v243, 41
	v_readlane_b32 s76, v242, 42
	v_readlane_b32 s77, v243, 42
	v_readlane_b32 s78, v242, 43
	v_readlane_b32 s79, v243, 43
	v_cmp_gt_u64_e64 vcc, s[72:73], v[242:243]
	v_cmp_gt_u64_e64 s[0:1], s[74:75], v[242:243]
	v_cmp_gt_u64_e64 s[2:3], s[76:77], v[242:243]
	v_cmp_gt_u64_e64 s[4:5], s[78:79], v[242:243]
	v_addc_co_u32_e64 v36, vcc, 0, v36, vcc
	v_addc_co_u32_e64 v187, s[0:1], 0, v187, s[0:1]
	v_addc_co_u32_e64 v36, s[2:3], 0, v36, s[2:3]
	v_addc_co_u32_e64 v187, s[4:5], 0, v187, s[4:5]
	s_cmpk_le_u32 s82, 44
	s_cbranch_scc1 .Lsel_rank_done
	v_readlane_b32 s72, v242, 44
	v_readlane_b32 s73, v243, 44
	v_readlane_b32 s74, v242, 45
	v_readlane_b32 s75, v243, 45
	v_readlane_b32 s76, v242, 46
	v_readlane_b32 s77, v243, 46
	v_readlane_b32 s78, v242, 47
	v_readlane_b32 s79, v243, 47
	v_cmp_gt_u64_e64 vcc, s[72:73], v[242:243]
	v_cmp_gt_u64_e64 s[0:1], s[74:75], v[242:243]
	v_cmp_gt_u64_e64 s[2:3], s[76:77], v[242:243]
	v_cmp_gt_u64_e64 s[4:5], s[78:79], v[242:243]
	v_addc_co_u32_e64 v36, vcc, 0, v36, vcc
	v_addc_co_u32_e64 v187, s[0:1], 0, v187, s[0:1]
	v_addc_co_u32_e64 v36, s[2:3], 0, v36, s[2:3]
	v_addc_co_u32_e64 v187, s[4:5], 0, v187, s[4:5]
	s_cmpk_le_u32 s82, 48
	s_cbranch_scc1 .Lsel_rank_done
	v_readlane_b32 s72, v242, 48
	v_readlane_b32 s73, v243, 48
	v_readlane_b32 s74, v242, 49
	v_readlane_b32 s75, v243, 49
	v_readlane_b32 s76, v242, 50
	v_readlane_b32 s77, v243, 50
	v_readlane_b32 s78, v242, 51
	v_readlane_b32 s79, v243, 51
	v_cmp_gt_u64_e64 vcc, s[72:73], v[242:243]
	v_cmp_gt_u64_e64 s[0:1], s[74:75], v[242:243]
	v_cmp_gt_u64_e64 s[2:3], s[76:77], v[242:243]
	v_cmp_gt_u64_e64 s[4:5], s[78:79], v[242:243]
	v_addc_co_u32_e64 v36, vcc, 0, v36, vcc
	v_addc_co_u32_e64 v187, s[0:1], 0, v187, s[0:1]
	v_addc_co_u32_e64 v36, s[2:3], 0, v36, s[2:3]
	v_addc_co_u32_e64 v187, s[4:5], 0, v187, s[4:5]
	s_cmpk_le_u32 s82, 52
	s_cbranch_scc1 .Lsel_rank_done
	v_readlane_b32 s72, v242, 52
	v_readlane_b32 s73, v243, 52
	v_readlane_b32 s74, v242, 53
	v_readlane_b32 s75, v243, 53
	v_readlane_b32 s76, v242, 54
	v_readlane_b32 s77, v243, 54
	v_readlane_b32 s78, v242, 55
	v_readlane_b32 s79, v243, 55
	v_cmp_gt_u64_e64 vcc, s[72:73], v[242:243]
	v_cmp_gt_u64_e64 s[0:1], s[74:75], v[242:243]
	v_cmp_gt_u64_e64 s[2:3], s[76:77], v[242:243]
	v_cmp_gt_u64_e64 s[4:5], s[78:79], v[242:243]
	v_addc_co_u32_e64 v36, vcc, 0, v36, vcc
	v_addc_co_u32_e64 v187, s[0:1], 0, v187, s[0:1]
	v_addc_co_u32_e64 v36, s[2:3], 0, v36, s[2:3]
	v_addc_co_u32_e64 v187, s[4:5], 0, v187, s[4:5]
	s_cmpk_le_u32 s82, 56
	s_cbranch_scc1 .Lsel_rank_done
	v_readlane_b32 s72, v242, 56
	v_readlane_b32 s73, v243, 56
	v_readlane_b32 s74, v242, 57
	v_readlane_b32 s75, v243, 57
	v_readlane_b32 s76, v242, 58
	v_readlane_b32 s77, v243, 58
	v_readlane_b32 s78, v242, 59
	v_readlane_b32 s79, v243, 59
	v_cmp_gt_u64_e64 vcc, s[72:73], v[242:243]
	v_cmp_gt_u64_e64 s[0:1], s[74:75], v[242:243]
	v_cmp_gt_u64_e64 s[2:3], s[76:77], v[242:243]
	v_cmp_gt_u64_e64 s[4:5], s[78:79], v[242:243]
	v_addc_co_u32_e64 v36, vcc, 0, v36, vcc
	v_addc_co_u32_e64 v187, s[0:1], 0, v187, s[0:1]
	v_addc_co_u32_e64 v36, s[2:3], 0, v36, s[2:3]
	v_addc_co_u32_e64 v187, s[4:5], 0, v187, s[4:5]
	s_cmpk_le_u32 s82, 60
	s_cbranch_scc1 .Lsel_rank_done
	v_readlane_b32 s72, v242, 60
	v_readlane_b32 s73, v243, 60
	v_readlane_b32 s74, v242, 61
	v_readlane_b32 s75, v243, 61
	v_readlane_b32 s76, v242, 62
	v_readlane_b32 s77, v243, 62
	v_readlane_b32 s78, v242, 63
	v_readlane_b32 s79, v243, 63
	v_cmp_gt_u64_e64 vcc, s[72:73], v[242:243]
	v_cmp_gt_u64_e64 s[0:1], s[74:75], v[242:243]
	v_cmp_gt_u64_e64 s[2:3], s[76:77], v[242:243]
	v_cmp_gt_u64_e64 s[4:5], s[78:79], v[242:243]
	v_addc_co_u32_e64 v36, vcc, 0, v36, vcc
	v_addc_co_u32_e64 v187, s[0:1], 0, v187, s[0:1]
	v_addc_co_u32_e64 v36, s[2:3], 0, v36, s[2:3]
	v_addc_co_u32_e64 v187, s[4:5], 0, v187, s[4:5]
.Lsel_rank_done:
	v_add_u32_e32 v36, v36, v187
	v_cmp_gt_u32_e32 vcc, s81, v36
	v_cmp_gt_u32_e64 s[0:1], s82, v198
	v_and_b32_e32 v193, 4, v248
	v_lshlrev_b32_e32 v193, 3, v193
	v_lshrrev_b32_e32 v187, 8, v248
	v_lshl_add_u32 v193, v187, 2, v193
	v_bfe_u32 v194, v248, 6, 2
	v_add_u32_e32 v193, v193, v194
	s_and_b32 s7, s28, 7
	s_lshl_b32 s7, s7, 8
	s_add_i32 s7, s7, 0xc000
	s_nop 1
	v_lshl_add_u32 v193, v193, 2, s7
	v_bfe_u32 v194, v248, 3, 3
	v_and_b32_e32 v192, 3, v248
	v_lshl_add_u32 v194, v194, 2, v192
	v_lshlrev_b32_e32 v194, v194, v233
	s_and_b64 s[0:1], s[0:1], vcc
	s_mov_b64 exec, s[0:1]
	ds_or_b32 v193, v194
	s_mov_b64 exec, -1
